# gate scans moved from side workgroups 192..223 to wave 0 of the four-round GEMM workgroups 128..159, so every side workgroup reaches its first decode item sooner
# speedup vs baseline: 1.0055x; 1.0055x over previous
.LBB0_412:
	s_cmp_ge_i32 s12, s15
	s_cselect_b64 s[72:73], -1, 0
	s_cmp_lt_u32 s90, 64
	s_cselect_b64 s[0:1], -1, 0
	s_cmpk_ge_i32 s12, 0x80
	s_cselect_b64 s[2:3], -1, 0
	s_and_b64 s[0:1], s[2:3], s[0:1]
	s_cmpk_lt_i32 s12, 0xa0
	s_cselect_b64 s[2:3], -1, 0
	s_and_b64 s[0:1], s[0:1], s[2:3]
	s_andn2_b64 vcc, exec, s[0:1]
	s_cbranch_vccnz .LBB0_414
	s_add_i32 s4, s12, 0xffffff80
	s_and_b32 s0, s4, 3
	s_lshr_b32 s8, s4, 2
	s_lshl_b32 s0, s0, 2
	s_mov_b32 s9, 0
	s_add_u32 s0, s86, s0
	s_addc_u32 s1, s87, 0
	s_lshl_b64 s[2:3], s[8:9], 16
	s_waitcnt vmcnt(0)
	v_lshl_or_b32 v2, v214, 10, s2
	s_waitcnt lgkmcnt(0)
	v_mov_b32_e32 v3, s3
	v_lshl_add_u64 v[34:35], s[0:1], 0, v[2:3]
	global_load_dword v1, v[34:35], off offset:16
	global_load_dword v36, v[34:35], off offset:48
	global_load_dword v37, v[34:35], off offset:80
	global_load_dword v38, v[34:35], off offset:112
	global_load_dword v39, v[34:35], off offset:144
	global_load_dword v40, v[34:35], off offset:176
	global_load_dword v41, v[34:35], off offset:208
	global_load_dword v42, v[34:35], off offset:240
	global_load_dword v43, v[34:35], off offset:272
	global_load_dword v44, v[34:35], off offset:304
	global_load_dword v45, v[34:35], off offset:336
	global_load_dword v46, v[34:35], off offset:368
	global_load_dword v47, v[34:35], off offset:400
	global_load_dword v48, v[34:35], off offset:432
	global_load_dword v49, v[34:35], off offset:464
	global_load_dword v50, v[34:35], off offset:496
	global_load_dword v51, v[34:35], off offset:528
	global_load_dword v52, v[34:35], off offset:560
	global_load_dword v53, v[34:35], off offset:592
	global_load_dword v54, v[34:35], off offset:624
	global_load_dword v55, v[34:35], off offset:656
	global_load_dword v56, v[34:35], off offset:688
	global_load_dword v57, v[34:35], off offset:720
	global_load_dword v58, v[34:35], off offset:752
	global_load_dword v59, v[34:35], off offset:784
	global_load_dword v60, v[34:35], off offset:816
	global_load_dword v61, v[34:35], off offset:848
	global_load_dword v62, v[34:35], off offset:880
	global_load_dword v63, v[34:35], off offset:912
	global_load_dword v64, v[34:35], off offset:944
	global_load_dword v65, v[34:35], off offset:976
	global_load_dword v66, v[34:35], off offset:1008
	global_load_dword v27, v[34:35], off offset:96
	global_load_dword v26, v[34:35], off offset:64
	global_load_dword v33, v[34:35], off offset:32
	global_load_dword v32, v[34:35], off
	global_load_dword v23, v[34:35], off offset:224
	global_load_dword v22, v[34:35], off offset:192
	global_load_dword v31, v[34:35], off offset:160
	global_load_dword v30, v[34:35], off offset:128
	global_load_dword v19, v[34:35], off offset:352
	global_load_dword v18, v[34:35], off offset:320
	global_load_dword v29, v[34:35], off offset:288
	global_load_dword v28, v[34:35], off offset:256
	global_load_dword v15, v[34:35], off offset:480
	global_load_dword v14, v[34:35], off offset:448
	global_load_dword v25, v[34:35], off offset:416
	global_load_dword v24, v[34:35], off offset:384
	global_load_dword v11, v[34:35], off offset:608
	global_load_dword v10, v[34:35], off offset:576
	global_load_dword v21, v[34:35], off offset:544
	global_load_dword v20, v[34:35], off offset:512
	global_load_dword v7, v[34:35], off offset:736
	global_load_dword v6, v[34:35], off offset:704
	global_load_dword v17, v[34:35], off offset:672
	global_load_dword v16, v[34:35], off offset:640
	global_load_dword v3, v[34:35], off offset:864
	global_load_dword v2, v[34:35], off offset:832
	global_load_dword v13, v[34:35], off offset:800
	global_load_dword v12, v[34:35], off offset:768
	global_load_dword v5, v[34:35], off offset:992
	global_load_dword v4, v[34:35], off offset:960
	global_load_dword v9, v[34:35], off offset:928
	global_load_dword v8, v[34:35], off offset:896
	v_mbcnt_lo_u32_b32 v34, -1, 0
	v_mbcnt_hi_u32_b32 v67, -1, v34
	v_and_b32_e32 v68, 64, v67
	v_add_u32_e32 v34, -1, v67
	v_cmp_lt_i32_e32 vcc, v34, v68
	v_add_u32_e32 v69, -8, v67
	s_mov_b32 s5, s9
	v_cndmask_b32_e32 v34, v34, v67, vcc
	v_lshlrev_b32_e32 v120, 2, v34
	v_add_u32_e32 v34, -2, v67
	v_cmp_lt_i32_e32 vcc, v34, v68
	s_lshl_b64 s[4:5], s[4:5], 13
	v_cmp_gt_u32_e64 s[8:9], 16, v214
	v_cndmask_b32_e32 v34, v34, v67, vcc
	v_lshlrev_b32_e32 v83, 2, v34
	v_add_u32_e32 v34, -4, v67
	v_cmp_lt_i32_e32 vcc, v34, v68
	v_cmp_gt_u32_e64 s[10:11], 32, v214
	s_mov_b32 s6, 0xff800000
	v_cndmask_b32_e32 v34, v34, v67, vcc
	v_lshlrev_b32_e32 v102, 2, v34
	s_waitcnt vmcnt(62)
	v_add_f32_e32 v34, 0, v1
	v_add_f32_e32 v35, v34, v36
	s_waitcnt vmcnt(61)
	v_add_f32_e32 v36, v35, v37
	s_waitcnt vmcnt(60)
	v_add_f32_e32 v37, v36, v38
	s_waitcnt vmcnt(59)
	v_add_f32_e32 v38, v37, v39
	s_waitcnt vmcnt(58)
	v_add_f32_e32 v39, v38, v40
	s_waitcnt vmcnt(57)
	v_add_f32_e32 v40, v39, v41
	s_waitcnt vmcnt(56)
	v_add_f32_e32 v41, v40, v42
	s_waitcnt vmcnt(55)
	v_add_f32_e32 v42, v41, v43
	s_waitcnt vmcnt(54)
	v_add_f32_e32 v43, v42, v44
	s_waitcnt vmcnt(53)
	v_add_f32_e32 v44, v43, v45
	s_waitcnt vmcnt(52)
	v_add_f32_e32 v45, v44, v46
	s_waitcnt vmcnt(51)
	v_add_f32_e32 v46, v45, v47
	s_waitcnt vmcnt(50)
	v_add_f32_e32 v47, v46, v48
	s_waitcnt vmcnt(49)
	v_add_f32_e32 v48, v47, v49
	s_waitcnt vmcnt(48)
	v_add_f32_e32 v49, v48, v50
	s_waitcnt vmcnt(47)
	v_add_f32_e32 v50, v49, v51
	s_waitcnt vmcnt(46)
	v_add_f32_e32 v51, v50, v52
	s_waitcnt vmcnt(45)
	v_add_f32_e32 v52, v51, v53
	s_waitcnt vmcnt(44)
	v_add_f32_e32 v53, v52, v54
	s_waitcnt vmcnt(43)
	v_add_f32_e32 v54, v53, v55
	s_waitcnt vmcnt(42)
	v_add_f32_e32 v55, v54, v56
	s_waitcnt vmcnt(41)
	v_add_f32_e32 v56, v55, v57
	s_waitcnt vmcnt(40)
	v_add_f32_e32 v57, v56, v58
	s_waitcnt vmcnt(39)
	v_add_f32_e32 v58, v57, v59
	s_waitcnt vmcnt(38)
	v_add_f32_e32 v59, v58, v60
	s_waitcnt vmcnt(37)
	v_add_f32_e32 v60, v59, v61
	s_waitcnt vmcnt(36)
	v_add_f32_e32 v61, v60, v62
	s_waitcnt vmcnt(35)
	v_add_f32_e32 v62, v61, v63
	s_waitcnt vmcnt(34)
	v_add_f32_e32 v63, v62, v64
	s_waitcnt vmcnt(33)
	v_add_f32_e32 v64, v63, v65
	s_waitcnt vmcnt(32)
	v_add_f32_e32 v65, v64, v66
	ds_bpermute_b32 v1, v120, v65
	v_cmp_lt_i32_e32 vcc, v69, v68
	v_readlane_b32 s16, v245, 36
	v_readlane_b32 s18, v245, 38
	v_cndmask_b32_e32 v66, v69, v67, vcc
	s_waitcnt lgkmcnt(0)
	v_add_f32_e32 v1, v65, v1
	v_cmp_eq_u32_e32 vcc, 0, v214
	v_lshlrev_b32_e32 v106, 2, v66
	v_add_u32_e32 v66, -16, v67
	v_cndmask_b32_e32 v1, v1, v65, vcc
	ds_bpermute_b32 v69, v83, v1
	v_cmp_lt_i32_e64 s[0:1], v66, v68
	v_readlane_b32 s17, v245, 37
	v_readlane_b32 s19, v245, 39
	v_cndmask_b32_e64 v66, v66, v67, s[0:1]
	s_waitcnt lgkmcnt(0)
	v_add_f32_e32 v69, v1, v69
	v_cmp_gt_u32_e64 s[0:1], 2, v214
	v_lshlrev_b32_e32 v110, 2, v66
	v_subrev_u32_e32 v66, 32, v67
	v_cndmask_b32_e64 v1, v69, v1, s[0:1]
	ds_bpermute_b32 v69, v102, v1
	v_cmp_lt_i32_e64 s[2:3], v66, v68
	s_nop 1
	v_cndmask_b32_e64 v66, v66, v67, s[2:3]
	v_lshlrev_b32_e32 v114, 2, v66
	s_waitcnt lgkmcnt(0)
	v_add_f32_e32 v66, v1, v69
	v_cmp_gt_u32_e64 s[2:3], 4, v214
	v_mov_b32_e32 v67, s5
	v_mov_b32_e32 v81, v67
	v_cndmask_b32_e64 v1, v66, v1, s[2:3]
	ds_bpermute_b32 v72, v106, v1
	v_lshl_or_b32 v66, v214, 7, s4
	v_cmp_gt_u32_e64 s[4:5], 8, v214
	v_or_b32_e32 v80, 32, v66
	v_lshl_add_u64 v[68:69], s[62:63], 0, v[66:67]
	s_waitcnt lgkmcnt(0)
	v_add_f32_e32 v72, v1, v72
	v_cndmask_b32_e64 v1, v72, v1, s[4:5]
	ds_bpermute_b32 v78, v110, v1
	v_lshl_add_u64 v[70:71], s[16:17], 0, v[66:67]
	v_lshl_add_u64 v[72:73], s[18:19], 0, v[66:67]
	v_or_b32_e32 v74, 16, v66
	v_mov_b32_e32 v75, v67
	s_waitcnt lgkmcnt(0)
	v_add_f32_e32 v78, v1, v78
	v_cndmask_b32_e64 v1, v78, v1, s[8:9]
	ds_bpermute_b32 v82, v114, v1
	v_lshl_add_u64 v[76:77], s[62:63], 0, v[74:75]
	v_lshl_add_u64 v[78:79], s[16:17], 0, v[74:75]
	v_lshl_add_u64 v[74:75], s[18:19], 0, v[74:75]
	s_waitcnt lgkmcnt(0)
	v_add_f32_e32 v82, v1, v82
	v_cndmask_b32_e64 v1, v82, v1, s[10:11]
	v_sub_f32_e32 v82, v1, v65
	v_pk_add_f32 v[34:35], v[82:83], v[34:35] op_sel_hi:[0,1]
	s_waitcnt vmcnt(28)
	v_pk_add_f32 v[32:33], v[32:33], v[34:35] neg_lo:[0,1] neg_hi:[0,1]
	v_pk_add_f32 v[36:37], v[82:83], v[36:37] op_sel_hi:[0,1]
	v_max3_f32 v1, v32, s6, v33
	v_pk_add_f32 v[26:27], v[26:27], v[36:37] neg_lo:[0,1] neg_hi:[0,1]
	v_pk_add_f32 v[38:39], v[82:83], v[38:39] op_sel_hi:[0,1]
	v_max3_f32 v1, v1, v26, v27
	s_waitcnt vmcnt(24)
	v_pk_add_f32 v[30:31], v[30:31], v[38:39] neg_lo:[0,1] neg_hi:[0,1]
	v_pk_add_f32 v[40:41], v[82:83], v[40:41] op_sel_hi:[0,1]
	v_max3_f32 v1, v1, v30, v31
	v_pk_add_f32 v[84:85], v[22:23], v[40:41] neg_lo:[0,1] neg_hi:[0,1]
	v_pk_add_f32 v[42:43], v[82:83], v[42:43] op_sel_hi:[0,1]
	v_max3_f32 v1, v1, v84, v85
	s_waitcnt vmcnt(20)
	v_pk_add_f32 v[28:29], v[28:29], v[42:43] neg_lo:[0,1] neg_hi:[0,1]
	v_pk_add_f32 v[44:45], v[82:83], v[44:45] op_sel_hi:[0,1]
	v_max3_f32 v1, v1, v28, v29
	v_pk_add_f32 v[86:87], v[18:19], v[44:45] neg_lo:[0,1] neg_hi:[0,1]
	v_pk_add_f32 v[46:47], v[82:83], v[46:47] op_sel_hi:[0,1]
	v_max3_f32 v1, v1, v86, v87
	s_waitcnt vmcnt(16)
	v_pk_add_f32 v[88:89], v[24:25], v[46:47] neg_lo:[0,1] neg_hi:[0,1]
	v_pk_add_f32 v[48:49], v[82:83], v[48:49] op_sel_hi:[0,1]
	v_max3_f32 v1, v1, v88, v89
	v_pk_add_f32 v[90:91], v[14:15], v[48:49] neg_lo:[0,1] neg_hi:[0,1]
	v_pk_add_f32 v[50:51], v[82:83], v[50:51] op_sel_hi:[0,1]
	v_max3_f32 v1, v1, v90, v91
	s_waitcnt vmcnt(12)
	v_pk_add_f32 v[92:93], v[20:21], v[50:51] neg_lo:[0,1] neg_hi:[0,1]
	v_pk_add_f32 v[52:53], v[82:83], v[52:53] op_sel_hi:[0,1]
	v_max3_f32 v1, v1, v92, v93
	v_pk_add_f32 v[94:95], v[10:11], v[52:53] neg_lo:[0,1] neg_hi:[0,1]
	v_pk_add_f32 v[54:55], v[82:83], v[54:55] op_sel_hi:[0,1]
	v_max3_f32 v1, v1, v94, v95
	s_waitcnt vmcnt(8)
	v_pk_add_f32 v[96:97], v[16:17], v[54:55] neg_lo:[0,1] neg_hi:[0,1]
	v_pk_add_f32 v[56:57], v[82:83], v[56:57] op_sel_hi:[0,1]
	v_max3_f32 v1, v1, v96, v97
	v_pk_add_f32 v[98:99], v[6:7], v[56:57] neg_lo:[0,1] neg_hi:[0,1]
	v_pk_add_f32 v[14:15], v[82:83], v[58:59] op_sel_hi:[0,1]
	v_max3_f32 v1, v1, v98, v99
	s_waitcnt vmcnt(4)
	v_pk_add_f32 v[58:59], v[12:13], v[14:15] neg_lo:[0,1] neg_hi:[0,1]
	v_pk_add_f32 v[10:11], v[82:83], v[60:61] op_sel_hi:[0,1]
	v_max3_f32 v1, v1, v58, v59
	v_pk_add_f32 v[12:13], v[2:3], v[10:11] neg_lo:[0,1] neg_hi:[0,1]
	v_pk_add_f32 v[6:7], v[82:83], v[62:63] op_sel_hi:[0,1]
	v_max3_f32 v1, v1, v12, v13
	s_waitcnt vmcnt(0)
	v_pk_add_f32 v[8:9], v[8:9], v[6:7] neg_lo:[0,1] neg_hi:[0,1]
	v_pk_add_f32 v[2:3], v[82:83], v[64:65] op_sel_hi:[0,1]
	v_max3_f32 v1, v1, v8, v9
	v_pk_add_f32 v[4:5], v[4:5], v[2:3] neg_lo:[0,1] neg_hi:[0,1]
	v_or_b32_e32 v16, 48, v66
	v_max3_f32 v1, v1, v4, v5
	ds_bpermute_b32 v17, v120, v1
	v_lshl_add_u64 v[60:61], s[62:63], 0, v[80:81]
	v_lshl_add_u64 v[62:63], s[16:17], 0, v[80:81]
	v_lshl_add_u64 v[64:65], s[18:19], 0, v[80:81]
	s_waitcnt lgkmcnt(0)
	v_max_f32_e32 v17, v17, v17
	v_max_f32_e32 v17, v1, v17
	v_cndmask_b32_e32 v1, v17, v1, vcc
	ds_bpermute_b32 v18, v83, v1
	v_mov_b32_e32 v17, v67
	v_lshl_add_u64 v[80:81], s[62:63], 0, v[16:17]
	v_lshl_add_u64 v[82:83], s[16:17], 0, v[16:17]
	v_lshl_add_u64 v[100:101], s[18:19], 0, v[16:17]
	s_waitcnt lgkmcnt(0)
	v_max_f32_e32 v16, v18, v18
	v_max_f32_e32 v16, v1, v16
	v_cndmask_b32_e64 v1, v16, v1, s[0:1]
	ds_bpermute_b32 v18, v102, v1
	v_or_b32_e32 v16, 64, v66
	v_lshl_add_u64 v[102:103], s[62:63], 0, v[16:17]
	v_lshl_add_u64 v[104:105], s[16:17], 0, v[16:17]
	s_mov_b32 s0, 0x3fb8aa3b
	s_waitcnt lgkmcnt(0)
	v_max_f32_e32 v18, v18, v18
	v_max_f32_e32 v18, v1, v18
	v_cndmask_b32_e64 v1, v18, v1, s[2:3]
	ds_bpermute_b32 v18, v106, v1
	v_lshl_add_u64 v[106:107], s[18:19], 0, v[16:17]
	v_or_b32_e32 v16, 0x50, v66
	v_lshl_add_u64 v[108:109], s[62:63], 0, v[16:17]
	v_lshl_add_u64 v[112:113], s[18:19], 0, v[16:17]
	s_waitcnt lgkmcnt(0)
	v_max_f32_e32 v18, v18, v18
	v_max_f32_e32 v18, v1, v18
	v_cndmask_b32_e64 v1, v18, v1, s[4:5]
	ds_bpermute_b32 v18, v110, v1
	v_lshl_add_u64 v[110:111], s[16:17], 0, v[16:17]
	v_or_b32_e32 v16, 0x60, v66
	v_lshl_add_u64 v[116:117], s[16:17], 0, v[16:17]
	v_lshl_add_u64 v[118:119], s[18:19], 0, v[16:17]
	s_waitcnt lgkmcnt(0)
	v_max_f32_e32 v18, v18, v18
	v_max_f32_e32 v18, v1, v18
	v_cndmask_b32_e64 v1, v18, v1, s[8:9]
	ds_bpermute_b32 v18, v114, v1
	v_lshl_add_u64 v[114:115], s[62:63], 0, v[16:17]
	v_max_f32_e32 v16, v1, v1
	v_or_b32_e32 v66, 0x70, v66
	v_lshl_add_u64 v[122:123], s[16:17], 0, v[66:67]
	s_waitcnt lgkmcnt(0)
	v_max_f32_e32 v17, v18, v18
	v_max_f32_e32 v16, v16, v17
	v_cndmask_b32_e64 v1, v16, v1, s[10:11]
	ds_bpermute_b32 v1, v120, v1
	v_pk_mul_f32 v[16:17], v[32:33], s[0:1] op_sel_hi:[1,0]
	v_lshl_add_u64 v[120:121], s[62:63], 0, v[66:67]
	v_lshl_add_u64 v[66:67], s[18:19], 0, v[66:67]
	s_waitcnt lgkmcnt(0)
	v_max_f32_e32 v1, v1, v1
	v_max_f32_e32 v1, 0, v1
	v_cndmask_b32_e64 v1, v1, 0, vcc
	v_max_f32_e32 v18, v1, v32
	v_max_f32_e32 v19, v18, v33
	v_max_f32_e32 v32, v19, v26
	v_pk_mul_f32 v[20:21], v[18:19], s[0:1] op_sel_hi:[1,0]
	v_pk_add_f32 v[24:25], v[18:19], v[34:35]
	v_max_f32_e32 v33, v32, v27
	v_pk_mul_f32 v[18:19], v[26:27], s[0:1] op_sel_hi:[1,0]
	global_store_dwordx4 v[68:69], v[16:19], off
	v_pk_mul_f32 v[22:23], v[32:33], s[0:1] op_sel_hi:[1,0]
	v_pk_add_f32 v[26:27], v[32:33], v[36:37]
	v_max_f32_e32 v18, v33, v30
	v_max_f32_e32 v19, v18, v31
	v_pk_mul_f32 v[16:17], v[30:31], s[0:1] op_sel_hi:[1,0]
	v_max_f32_e32 v30, v19, v84
	global_store_dwordx4 v[70:71], v[20:23], off
	global_store_dwordx4 v[72:73], v[24:27], off
	v_max_f32_e32 v31, v30, v85
	v_pk_mul_f32 v[20:21], v[18:19], s[0:1] op_sel_hi:[1,0]
	v_pk_add_f32 v[24:25], v[18:19], v[38:39]
	v_pk_mul_f32 v[18:19], v[84:85], s[0:1] op_sel_hi:[1,0]
	global_store_dwordx4 v[76:77], v[16:19], off
	v_pk_mul_f32 v[22:23], v[30:31], s[0:1] op_sel_hi:[1,0]
	v_pk_add_f32 v[26:27], v[30:31], v[40:41]
	v_max_f32_e32 v18, v31, v28
	v_max_f32_e32 v19, v18, v29
	v_pk_mul_f32 v[16:17], v[28:29], s[0:1] op_sel_hi:[1,0]
	v_max_f32_e32 v28, v19, v86
	global_store_dwordx4 v[78:79], v[20:23], off
	global_store_dwordx4 v[74:75], v[24:27], off
	v_max_f32_e32 v29, v28, v87
	v_pk_mul_f32 v[20:21], v[18:19], s[0:1] op_sel_hi:[1,0]
	v_pk_add_f32 v[24:25], v[18:19], v[42:43]
	v_pk_mul_f32 v[18:19], v[86:87], s[0:1] op_sel_hi:[1,0]
	global_store_dwordx4 v[60:61], v[16:19], off
	v_pk_mul_f32 v[22:23], v[28:29], s[0:1] op_sel_hi:[1,0]
	v_pk_add_f32 v[26:27], v[28:29], v[44:45]
	v_max_f32_e32 v18, v29, v88
	v_max_f32_e32 v19, v18, v89
	v_max_f32_e32 v28, v19, v90
	global_store_dwordx4 v[62:63], v[20:23], off
	global_store_dwordx4 v[64:65], v[24:27], off
	v_pk_mul_f32 v[16:17], v[88:89], s[0:1] op_sel_hi:[1,0]
	v_pk_mul_f32 v[20:21], v[18:19], s[0:1] op_sel_hi:[1,0]
	v_pk_add_f32 v[24:25], v[18:19], v[46:47]
	v_max_f32_e32 v29, v28, v91
	v_pk_mul_f32 v[18:19], v[90:91], s[0:1] op_sel_hi:[1,0]
	global_store_dwordx4 v[80:81], v[16:19], off
	v_pk_mul_f32 v[22:23], v[28:29], s[0:1] op_sel_hi:[1,0]
	v_pk_add_f32 v[26:27], v[28:29], v[48:49]
	v_max_f32_e32 v18, v29, v92
	v_max_f32_e32 v19, v18, v93
	v_max_f32_e32 v28, v19, v94
	global_store_dwordx4 v[82:83], v[20:23], off
	global_store_dwordx4 v[100:101], v[24:27], off
	v_pk_mul_f32 v[16:17], v[92:93], s[0:1] op_sel_hi:[1,0]
	v_pk_mul_f32 v[20:21], v[18:19], s[0:1] op_sel_hi:[1,0]
	v_pk_add_f32 v[24:25], v[18:19], v[50:51]
	v_max_f32_e32 v29, v28, v95
	v_pk_mul_f32 v[18:19], v[94:95], s[0:1] op_sel_hi:[1,0]
	global_store_dwordx4 v[102:103], v[16:19], off
	v_pk_mul_f32 v[22:23], v[28:29], s[0:1] op_sel_hi:[1,0]
	v_pk_add_f32 v[26:27], v[28:29], v[52:53]
	v_max_f32_e32 v18, v29, v96
	v_max_f32_e32 v19, v18, v97
	v_max_f32_e32 v28, v19, v98
	global_store_dwordx4 v[104:105], v[20:23], off
	global_store_dwordx4 v[106:107], v[24:27], off
	v_pk_mul_f32 v[16:17], v[96:97], s[0:1] op_sel_hi:[1,0]
	v_pk_mul_f32 v[20:21], v[18:19], s[0:1] op_sel_hi:[1,0]
	v_pk_add_f32 v[24:25], v[18:19], v[54:55]
	v_max_f32_e32 v29, v28, v99
	v_pk_mul_f32 v[18:19], v[98:99], s[0:1] op_sel_hi:[1,0]
	global_store_dwordx4 v[108:109], v[16:19], off
	v_pk_add_f32 v[26:27], v[28:29], v[56:57]
	v_pk_mul_f32 v[22:23], v[28:29], s[0:1] op_sel_hi:[1,0]
	v_max_f32_e32 v18, v29, v58
	v_max_f32_e32 v19, v18, v59
	global_store_dwordx4 v[112:113], v[24:27], off
	global_store_dwordx4 v[110:111], v[20:23], off
	v_pk_mul_f32 v[16:17], v[58:59], s[0:1] op_sel_hi:[1,0]
	v_max_f32_e32 v24, v19, v12
	v_pk_mul_f32 v[20:21], v[18:19], s[0:1] op_sel_hi:[1,0]
	v_pk_add_f32 v[14:15], v[18:19], v[14:15]
	v_max_f32_e32 v25, v24, v13
	v_pk_mul_f32 v[18:19], v[12:13], s[0:1] op_sel_hi:[1,0]
	global_store_dwordx4 v[114:115], v[16:19], off
	v_pk_mul_f32 v[22:23], v[24:25], s[0:1] op_sel_hi:[1,0]
	global_store_dwordx4 v[116:117], v[20:23], off
	v_pk_add_f32 v[16:17], v[24:25], v[10:11]
	v_max_f32_e32 v10, v25, v8
	v_max_f32_e32 v11, v10, v9
	global_store_dwordx4 v[118:119], v[14:17], off
	v_pk_mul_f32 v[8:9], v[8:9], s[0:1] op_sel_hi:[1,0]
	v_pk_mul_f32 v[12:13], v[10:11], s[0:1] op_sel_hi:[1,0]
	v_max_f32_e32 v16, v11, v4
	v_pk_add_f32 v[6:7], v[10:11], v[6:7]
	v_max_f32_e32 v17, v16, v5
	v_pk_mul_f32 v[10:11], v[4:5], s[0:1] op_sel_hi:[1,0]
	global_store_dwordx4 v[120:121], v[8:11], off
	v_pk_mul_f32 v[14:15], v[16:17], s[0:1] op_sel_hi:[1,0]
	global_store_dwordx4 v[122:123], v[12:15], off
	v_pk_add_f32 v[8:9], v[16:17], v[2:3]
	global_store_dwordx4 v[66:67], v[6:9], off
